# re-tiled small-M path of P4/P6 with XCD-local column tiles (8 row blocks of one column tile share an XCD L2), on top of v23
# speedup vs baseline: 1.0084x; 1.0047x over previous
; #define LAS __attribute__((address_space(3)))
; __device__ __forceinline__ SmallId small_id() { int tid = threadIdx.x; asm volatile("" : "+v"(tid)); SmallId i; i.w = __builtin_amdgcn_readfirstlane(tid >> 6); i.fr = tid & 15; i.fq = (tid & 63) >> 4; i.row = MP + 16 * i.w + i.fr; return i; }
; template <int KSTEPS  >
; __device__ __forceinline__ void small_mma_ksplit(f32x4 (&acc)[2], const bf16_t* A, int lda, const bf16_t* Bt, int ldb, int n0, LAS unsigned char* lds, const SmallId& id) {
;     const int lane = id.fq * 16 + id.fr, k0 = id.w * (KSTEPS * 32);
;     f32x4 part[8][2];
; #pragma unroll
;     for (int rb = 0; rb < 8; ++rb) { part[rb][0] = (f32x4){0.f, 0.f, 0.f, 0.f}; part[rb][1] = part[rb][0]; }
;     const bf16_t* ap = A + (size_t)(MP + id.fr) * lda + k0 + 8 * id.fq;
;     const bf16_t* bp = Bt + (size_t)(n0 + id.fr) * ldb + k0 + 8 * id.fq;
; template <bool RES_F32, bool OUT_F32, int KSTEPS>
; __device__ __forceinline__ void small_res(const Params& p, LAS unsigned char* lds, const bf16_t* A, int lda, const bf16_t* Bt, int K, float* ssq_next, int G, int bx) {
;     const SmallId id = small_id();
;     bf16_t* XB = (bf16_t*)(p.ws + WS_XB);
;     for (int ts = G - 1 - bx; ts < DM / 32; ts += G) {
;         const int n0 = ts * 32; f32x4 acc[2] = {(f32x4){0.f, 0.f, 0.f, 0.f}, (f32x4){0.f, 0.f, 0.f, 0.f}};
;         small_mma_ksplit<KSTEPS>(acc, A, lda, Bt, K, n0, lds, id);
;         float s = 0.f;
; #pragma unroll
;         for (int nb = 0; nb < 2; ++nb) { const int col = n0 + 16 * nb + 4 * id.fq;
.LBB0_858:
	s_or_b64 exec, exec, s[0:1]
	v_readlane_b32 s0, v246, 16
	v_readlane_b32 s2, v246, 13
	s_add_u32 s40, s0, 0x880000
	v_readlane_b32 s0, v246, 17
	v_readlane_b32 s3, v246, 14
	s_addc_u32 s41, s0, 0
	s_and_b64 vcc, exec, s[2:3]
	v_readlane_b32 s2, v247, 8
	v_readlane_b32 s3, v247, 9
	s_mov_b64 s[0:1], -1
	s_waitcnt lgkmcnt(0)
	v_cndmask_b32_e64 v0, 0, 1, s[2:3]
	v_cmp_ne_u32_e64 s[2:3], 1, v0
	s_barrier
	s_nop 0
	v_writelane_b32 v246, s2, 22
	s_nop 1
	v_writelane_b32 v246, s3, 23
	s_cbranch_vccz .LBB0_903
	v_readlane_b32 s0, v246, 22
	s_add_u32 s2, s86, 0x60c00
	v_mov_b32_e32 v0, v222
	v_readlane_b32 s1, v246, 23
	s_addc_u32 s3, s87, 0
	s_and_b64 vcc, exec, s[0:1]
	v_readfirstlane_b32 s0, v0
	s_ashr_i32 s7, s0, 6
	s_lshl_b32 s0, s7, 4
	v_and_b32_e32 v4, 15, v0
	s_add_i32 s0, s0, 0x8000
	v_or_b32_e32 v2, s0, v4
	v_bfe_u32 v5, v0, 4, 2
	s_lshl_b32 s0, s7, 7
	s_lshl_b32 s8, s7, 14
	v_lshlrev_b32_e32 v0, 4, v0
	s_lshl_b32 s7, s7, 11
	s_add_i32 s8, s8, 0
	v_and_b32_e32 v0, 0x3f0, v0
	s_add_i32 s7, s7, 0
	v_add_u32_e32 v76, s8, v0
	s_add_i32 s8, s7, 0x10400
	s_ashr_i32 s1, s0, 31
	v_add_u32_e32 v79, s8, v0
	s_add_i32 s8, s7, 0x14400
	v_add_u32_e32 v77, s7, v0
	v_add_u32_e32 v81, s8, v0
	s_add_i32 s8, s7, 0x18400
	s_add_i32 s7, s7, 0x1c400
	s_lshl_b64 s[0:1], s[0:1], 1
	s_add_u32 s0, s86, s0
	v_add_u32_e32 v85, s7, v0
	s_addc_u32 s1, s87, s1
	s_mul_i32 s7, s93, 0x1b00000
	v_add_u32_e32 v83, s8, v0
	s_add_u32 s8, s0, s7
	v_ashrrev_i32_e32 v3, 31, v2
	v_lshlrev_b32_e32 v96, 4, v5
	s_addc_u32 s9, s1, 0
	v_lshlrev_b64 v[0:1], 11, v[2:3]
	v_lshl_add_u64 v[68:69], s[8:9], 0, v[96:97]
	v_readlane_b32 s7, v246, 8
	s_lshr_b32 s32, s7, 6
	s_and_b32 s7, s7, 7
	s_lshl_b32 s7, s7, 2
	s_add_i32 s7, s7, s32
	s_lshl_b32 s7, s7, 5
	v_lshl_or_b32 v96, v4, 11, v96
	v_add_u32_e32 v78, 0x10000, v77
	v_add_u32_e32 v80, 0x14000, v77
	v_add_u32_e32 v82, 0x18000, v77
	v_add_u32_e32 v84, 0x1c000, v77
	v_lshlrev_b32_e32 v86, 2, v5
	v_lshl_add_u64 v[64:65], s[90:91], 0, v[0:1]
	v_cmp_eq_u32_e32 vcc, 0, v5
	v_lshl_add_u64 v[66:67], v[2:3], 2, s[2:3]
	v_add_u32_e32 v70, s7, v4
	v_lshl_add_u64 v[72:73], s[0:1], 0, v[96:97]
	v_readlane_b32 s7, v246, 8
	s_lshr_b32 s32, s7, 6
	s_and_b32 s7, s7, 7
	s_lshl_b32 s7, s7, 2
	s_add_i32 s7, s7, s32
	s_branch .LBB0_862

; template <int KSTEPS  >
; __device__ __forceinline__ void small_mma_ksplit(f32x4 (&acc)[2], const bf16_t* A, int lda, const bf16_t* Bt, int ldb, int n0, LAS unsigned char* lds, const SmallId& id) {
;     const int lane = id.fq * 16 + id.fr, k0 = id.w * (KSTEPS * 32);
;     f32x4 part[8][2];
; #pragma unroll
;     for (int rb = 0; rb < 8; ++rb) { part[rb][0] = (f32x4){0.f, 0.f, 0.f, 0.f}; part[rb][1] = part[rb][0]; }
;     const bf16_t* ap = A + (size_t)(MP + id.fr) * lda + k0 + 8 * id.fq;
;     const bf16_t* bp = Bt + (size_t)(n0 + id.fr) * ldb + k0 + 8 * id.fq;
; #pragma unroll 1
;     for (int ks = 0; ks < KSTEPS; ++ks) {
;         bf16x8 a[8], b[2];
; #pragma unroll
;         for (int rb = 0; rb < 8; ++rb) a[rb] = *(const bf16x8*)(ap + (size_t)(16 * rb) * lda + 32 * ks);
;         b[0] = *(const bf16x8*)(bp + 32 * ks); b[1] = *(const bf16x8*)(bp + (size_t)16 * ldb + 32 * ks);
; #pragma unroll
;         for (int rb = 0; rb < 8; ++rb) { part[rb][0] = __builtin_amdgcn_mfma_f32_16x16x32_bf16(b[0], a[rb], part[rb][0], 0, 0, 0); part[rb][1] = __builtin_amdgcn_mfma_f32_16x16x32_bf16(b[1], a[rb], part[rb][1], 0, 0, 0); }
;     }
;     LAS f32x4* red = (LAS f32x4*)lds;
; #pragma unroll
;     for (int rb = 0; rb < 8; ++rb) { red[((id.w * 8 + rb) * 2 + 0) * 64 + lane] = part[rb][0]; red[((id.w * 8 + rb) * 2 + 1) * 64 + lane] = part[rb][1]; }
;     asm volatile("s_waitcnt lgkmcnt(0)" ::: "memory"); __syncthreads();
;     acc[0] = (f32x4){0.f, 0.f, 0.f, 0.f}; acc[1] = acc[0];
; #pragma unroll
;     for (int w2 = 0; w2 < 8; ++w2) { acc[0] += red[((w2 * 8 + id.w) * 2 + 0) * 64 + lane]; acc[1] += red[((w2 * 8 + id.w) * 2 + 1) * 64 + lane]; }
;     asm volatile("s_waitcnt lgkmcnt(0)" ::: "memory"); __syncthreads();
; template <bool RES_F32, bool OUT_F32, int KSTEPS>
; __device__ __forceinline__ void small_res(const Params& p, LAS unsigned char* lds, const bf16_t* A, int lda, const bf16_t* Bt, int K, float* ssq_next, int G, int bx) {
;     ...
;         float s = 0.f;
; #pragma unroll
;         for (int nb = 0; nb < 2; ++nb) { const int col = n0 + 16 * nb + 4 * id.fq;
;             f32x4 r;
;             if (RES_F32) r = *(const f32x4*)(p.xs + (size_t)(id.row - MP) * DM + col);
;             else { const u32x2 w = *(const u32x2*)(XB + (size_t)id.row * DM + col); r = (f32x4){bf_lo(w.x), bf_hi(w.x), bf_lo(w.y), bf_hi(w.y)}; }
;             const f32x4 x = r + acc[nb];
.LBB0_863:
	s_waitcnt lgkmcnt(0)
	v_readlane_b32 s8, v246, 8
	v_readfirstlane_b32 s32, v222
	s_bfe_u32 s8, s8, 0x30003
	s_lshr_b32 s32, s32, 6
	s_cmp_eq_u32 s32, s8
	s_cselect_b32 s32, 1, 0
	s_lshl_b32 s9, s8, 11
	v_add_u32_e32 v68, s9, v76
	s_sub_i32 s9, s11, s10
	s_mul_i32 s8, s8, s9
	s_add_i32 s8, s8, s10
	s_mov_b32 s9, 0
	v_lshl_add_u64 v[70:71], v[72:73], 0, s[8:9]
	s_mov_b32 s8, s18
	v_lshl_add_u64 v[88:89], v[74:75], 0, s[8:9]
	s_mov_b32 s8, s19
	v_lshl_add_u64 v[90:91], v[74:75], 0, s[8:9]
	global_load_dwordx4 v[92:95], v[70:71], off
	global_load_dwordx4 v[98:101], v[88:89], off
	global_load_dwordx4 v[102:105], v[90:91], off
	global_load_dwordx4 v[106:109], v[70:71], off offset:64
	global_load_dwordx4 v[110:113], v[88:89], off offset:64
	global_load_dwordx4 v[114:117], v[90:91], off offset:64
	global_load_dwordx4 v[118:121], v[70:71], off offset:128
	global_load_dwordx4 v[122:125], v[88:89], off offset:128
	global_load_dwordx4 v[126:129], v[90:91], off offset:128
	global_load_dwordx4 v[130:133], v[70:71], off offset:192
	global_load_dwordx4 v[134:137], v[88:89], off offset:192
	global_load_dwordx4 v[138:141], v[90:91], off offset:192
	s_waitcnt vmcnt(9)
	v_mfma_f32_16x16x32_bf16 v[36:39], v[98:101], v[92:95], v[36:39]
	v_mfma_f32_16x16x32_bf16 v[24:27], v[102:105], v[92:95], v[24:27]
	s_waitcnt vmcnt(6)
	v_mfma_f32_16x16x32_bf16 v[36:39], v[110:113], v[106:109], v[36:39]
	v_mfma_f32_16x16x32_bf16 v[24:27], v[114:117], v[106:109], v[24:27]
	s_waitcnt vmcnt(3)
	v_mfma_f32_16x16x32_bf16 v[36:39], v[122:125], v[118:121], v[36:39]
	v_mfma_f32_16x16x32_bf16 v[24:27], v[126:129], v[118:121], v[24:27]
	s_waitcnt vmcnt(0)
	v_mfma_f32_16x16x32_bf16 v[36:39], v[134:137], v[130:133], v[36:39]
	v_mfma_f32_16x16x32_bf16 v[24:27], v[138:141], v[130:133], v[24:27]
	s_nop 7
	s_nop 1
	ds_write_b128 v68, v[36:39]
	ds_write_b128 v68, v[24:27] offset:1024
	s_waitcnt lgkmcnt(0)
	s_waitcnt lgkmcnt(0)
	s_barrier
	ds_read_b128 v[0:3], v77
	s_waitcnt lgkmcnt(0)
	v_pk_add_f32 v[4:5], v[2:3], 0 op_sel_hi:[1,0]
	v_pk_add_f32 v[6:7], v[0:1], 0 op_sel_hi:[1,0]
	ds_read_b128 v[0:3], v77 offset:1024
	s_waitcnt lgkmcnt(0)
	v_pk_add_f32 v[8:9], v[2:3], 0 op_sel_hi:[1,0]
	v_pk_add_f32 v[10:11], v[0:1], 0 op_sel_hi:[1,0]
	ds_read_b128 v[0:3], v77 offset:16384
	s_waitcnt lgkmcnt(0)
	v_pk_add_f32 v[4:5], v[4:5], v[2:3]
	v_pk_add_f32 v[6:7], v[6:7], v[0:1]
	ds_read_b128 v[0:3], v77 offset:17408
	s_waitcnt lgkmcnt(0)
	v_pk_add_f32 v[8:9], v[8:9], v[2:3]
	v_pk_add_f32 v[10:11], v[10:11], v[0:1]
	ds_read_b128 v[0:3], v77 offset:32768
	s_waitcnt lgkmcnt(0)
	v_pk_add_f32 v[4:5], v[4:5], v[2:3]
	v_pk_add_f32 v[6:7], v[6:7], v[0:1]
	ds_read_b128 v[0:3], v77 offset:33792
	s_waitcnt lgkmcnt(0)
	v_pk_add_f32 v[8:9], v[8:9], v[2:3]
	v_pk_add_f32 v[10:11], v[10:11], v[0:1]
	ds_read_b128 v[0:3], v77 offset:49152
	s_waitcnt lgkmcnt(0)
	v_pk_add_f32 v[4:5], v[4:5], v[2:3]
	v_pk_add_f32 v[6:7], v[6:7], v[0:1]
	ds_read_b128 v[0:3], v77 offset:50176
	s_waitcnt lgkmcnt(0)
	v_pk_add_f32 v[8:9], v[8:9], v[2:3]
	v_pk_add_f32 v[10:11], v[10:11], v[0:1]
	ds_read_b128 v[0:3], v78
	s_waitcnt lgkmcnt(0)
	v_pk_add_f32 v[4:5], v[4:5], v[2:3]
	v_pk_add_f32 v[6:7], v[6:7], v[0:1]
	ds_read_b128 v[0:3], v79
	s_waitcnt lgkmcnt(0)
	v_pk_add_f32 v[8:9], v[8:9], v[2:3]
	v_pk_add_f32 v[10:11], v[10:11], v[0:1]
	ds_read_b128 v[0:3], v80
	s_waitcnt lgkmcnt(0)
	v_pk_add_f32 v[4:5], v[4:5], v[2:3]
	v_pk_add_f32 v[6:7], v[6:7], v[0:1]
	ds_read_b128 v[0:3], v81
	s_waitcnt lgkmcnt(0)
	v_pk_add_f32 v[8:9], v[8:9], v[2:3]
	v_pk_add_f32 v[10:11], v[10:11], v[0:1]
	ds_read_b128 v[0:3], v82
	s_waitcnt lgkmcnt(0)
	v_pk_add_f32 v[4:5], v[4:5], v[2:3]
	v_pk_add_f32 v[6:7], v[6:7], v[0:1]
	ds_read_b128 v[0:3], v83
	s_waitcnt lgkmcnt(0)
	v_pk_add_f32 v[8:9], v[8:9], v[2:3]
	v_pk_add_f32 v[10:11], v[10:11], v[0:1]
	ds_read_b128 v[0:3], v84
	s_waitcnt lgkmcnt(0)
	v_pk_add_f32 v[4:5], v[4:5], v[2:3]
	v_pk_add_f32 v[6:7], v[6:7], v[0:1]
	ds_read_b128 v[0:3], v85
	s_waitcnt lgkmcnt(0)
	s_waitcnt lgkmcnt(0)
	s_barrier
	s_mul_i32 exec_lo, s32, -1
	s_mov_b32 exec_hi, exec_lo
	v_pk_add_f32 v[2:3], v[8:9], v[2:3]
	v_lshl_or_b32 v8, s7, 5, v86
	v_ashrrev_i32_e32 v9, 31, v8
	v_lshl_add_u64 v[8:9], v[8:9], 1, v[64:65]
	v_pk_add_f32 v[0:1], v[10:11], v[0:1]
	global_load_dwordx2 v[10:11], v[8:9], off
	s_waitcnt vmcnt(0) lgkmcnt(0)
	v_lshlrev_b32_e32 v12, 16, v10
	v_and_b32_e32 v13, 0xffff0000, v10
	v_lshlrev_b32_e32 v10, 16, v11
	v_and_b32_e32 v11, 0xffff0000, v11
	v_pk_add_f32 v[4:5], v[4:5], v[10:11]
	v_pk_add_f32 v[6:7], v[6:7], v[12:13]
	s_nop 0
	v_cvt_pk_bf16_f32 v10, v6, v7
	v_cvt_pk_bf16_f32 v11, v4, v5
	v_mul_f32_e32 v7, v7, v7
	v_mul_f32_e32 v5, v5, v5
	v_fmac_f32_e32 v7, v6, v6
	v_fmac_f32_e32 v5, v4, v4
	global_store_dwordx2 v[8:9], v[10:11], off
	v_add_f32_e32 v10, v7, v5
	global_load_dwordx2 v[4:5], v[8:9], off offset:32
	s_waitcnt vmcnt(0) lgkmcnt(0)
	v_lshlrev_b32_e32 v6, 16, v4
	v_and_b32_e32 v7, 0xffff0000, v4
	v_lshlrev_b32_e32 v4, 16, v5
	v_and_b32_e32 v5, 0xffff0000, v5
	v_pk_add_f32 v[0:1], v[0:1], v[6:7]
	v_pk_add_f32 v[2:3], v[2:3], v[4:5]
	v_cvt_pk_bf16_f32 v4, v0, v1
	v_mul_f32_e32 v1, v1, v1
	v_fmac_f32_e32 v1, v0, v0
	v_mul_f32_e32 v0, v3, v3
	v_cvt_pk_bf16_f32 v5, v2, v3
	v_fmac_f32_e32 v0, v2, v2
	v_and_b32_e32 v2, 64, v225
	v_add_f32_e32 v0, v1, v0
	v_xor_b32_e32 v1, 16, v225
	v_add_u32_e32 v2, 64, v2
	v_cmp_lt_i32_e64 s[0:1], v1, v2
	v_add_f32_e32 v0, v10, v0
	global_store_dwordx2 v[8:9], v[4:5], off offset:32
	v_cndmask_b32_e64 v1, v225, v1, s[0:1]
	v_lshlrev_b32_e32 v1, 2, v1
	ds_bpermute_b32 v1, v1, v0
	s_waitcnt lgkmcnt(0)
	v_add_f32_e32 v0, v0, v1
	v_xor_b32_e32 v1, 32, v225
	v_cmp_lt_i32_e64 s[0:1], v1, v2
	s_nop 1
	v_cndmask_b32_e64 v1, v225, v1, s[0:1]
	v_lshlrev_b32_e32 v1, 2, v1
	ds_bpermute_b32 v1, v1, v0
	s_and_saveexec_b64 s[0:1], vcc
	s_cbranch_execz .LBB0_861
	s_waitcnt lgkmcnt(0)
	v_add_f32_e32 v0, v0, v1
	global_atomic_add_f32 v[66:67], v0, off
	s_branch .LBB0_861

; #define LAS __attribute__((address_space(3)))
; __device__ __forceinline__ SmallId small_id() { int tid = threadIdx.x; asm volatile("" : "+v"(tid)); SmallId i; i.w = __builtin_amdgcn_readfirstlane(tid >> 6); i.fr = tid & 15; i.fq = (tid & 63) >> 4; i.row = MP + 16 * i.w + i.fr; return i; }
; template <int KSTEPS  >
; __device__ __forceinline__ void small_mma_ksplit(f32x4 (&acc)[2], const bf16_t* A, int lda, const bf16_t* Bt, int ldb, int n0, LAS unsigned char* lds, const SmallId& id) {
;     const int lane = id.fq * 16 + id.fr, k0 = id.w * (KSTEPS * 32);
;     f32x4 part[8][2];
; #pragma unroll
;     for (int rb = 0; rb < 8; ++rb) { part[rb][0] = (f32x4){0.f, 0.f, 0.f, 0.f}; part[rb][1] = part[rb][0]; }
;     const bf16_t* ap = A + (size_t)(MP + id.fr) * lda + k0 + 8 * id.fq;
;     const bf16_t* bp = Bt + (size_t)(n0 + id.fr) * ldb + k0 + 8 * id.fq;
; template <bool RES_F32, bool OUT_F32, int KSTEPS>
; __device__ __forceinline__ void small_res(const Params& p, LAS unsigned char* lds, const bf16_t* A, int lda, const bf16_t* Bt, int K, float* ssq_next, int G, int bx) {
;     const SmallId id = small_id();
;     bf16_t* XB = (bf16_t*)(p.ws + WS_XB);
;     for (int ts = G - 1 - bx; ts < DM / 32; ts += G) {
;         const int n0 = ts * 32; f32x4 acc[2] = {(f32x4){0.f, 0.f, 0.f, 0.f}, (f32x4){0.f, 0.f, 0.f, 0.f}};
;         small_mma_ksplit<KSTEPS>(acc, A, lda, Bt, K, n0, lds, id);
;         float s = 0.f;
; #pragma unroll
;         for (int nb = 0; nb < 2; ++nb) { const int col = n0 + 16 * nb + 4 * id.fq;
.LBB0_903:
	s_and_b64 vcc, exec, s[0:1]
	s_cbranch_vccz .LBB0_947
	v_readlane_b32 s0, v246, 22
	s_add_u32 s2, s86, 0x20400
	v_mov_b32_e32 v0, v222
	v_readlane_b32 s1, v246, 23
	s_addc_u32 s3, s87, 0
	s_and_b64 vcc, exec, s[0:1]
	v_readfirstlane_b32 s0, v0
	s_ashr_i32 s7, s0, 6
	s_lshl_b32 s0, s7, 4
	v_and_b32_e32 v6, 15, v0
	s_add_i32 s0, s0, 0x8000
	v_or_b32_e32 v2, s0, v6
	v_bfe_u32 v7, v0, 4, 2
	s_lshl_b32 s0, s7, 7
	s_lshl_b32 s8, s7, 14
	v_lshlrev_b32_e32 v0, 4, v0
	s_lshl_b32 s7, s7, 11
	s_add_i32 s8, s8, 0
	v_and_b32_e32 v0, 0x3f0, v0
	s_add_i32 s7, s7, 0
	v_add_u32_e32 v78, s8, v0
	s_add_i32 s8, s7, 0x10400
	v_add_u32_e32 v81, s8, v0
	s_add_i32 s8, s7, 0x14400
	v_add_u32_e32 v83, s8, v0
	s_add_i32 s8, s7, 0x18400
	s_ashr_i32 s1, s0, 31
	v_add_u32_e32 v85, s8, v0
	v_readlane_b32 s8, v249, 4
	v_add_u32_e32 v79, s7, v0
	s_add_i32 s7, s7, 0x1c400
	v_ashrrev_i32_e32 v3, 31, v2
	v_readlane_b32 s9, v249, 5
	s_lshl_b64 s[0:1], s[0:1], 1
	v_add_u32_e32 v87, s7, v0
	s_waitcnt lgkmcnt(0)
	v_lshlrev_b64 v[0:1], 12, v[2:3]
	v_readlane_b32 s10, v249, 6
	v_readlane_b32 s11, v249, 7
	s_brev_b32 s8, 31
	s_add_u32 s0, s86, s0
	v_lshl_add_u64 v[0:1], s[10:11], 0, v[0:1]
	s_mov_b32 s9, -1
	s_addc_u32 s1, s87, s1
	s_mul_i32 s7, s93, 0x1b00000
	v_lshl_add_u64 v[68:69], v[0:1], 0, s[8:9]
	s_add_u32 s8, s0, s7
	v_lshlrev_b32_e32 v96, 4, v7
	s_addc_u32 s9, s1, 0
	v_lshlrev_b64 v[4:5], 11, v[2:3]
	v_lshl_add_u64 v[70:71], s[8:9], 0, v[96:97]
	v_readlane_b32 s7, v246, 8
	s_lshr_b32 s32, s7, 6
	s_and_b32 s7, s7, 7
	s_lshl_b32 s7, s7, 2
	s_add_i32 s7, s7, s32
	s_lshl_b32 s7, s7, 5
	v_lshl_or_b32 v96, v6, 11, v96
	v_add_u32_e32 v80, 0x10000, v79
	v_add_u32_e32 v82, 0x14000, v79
	v_add_u32_e32 v84, 0x18000, v79
	v_add_u32_e32 v86, 0x1c000, v79
	v_lshlrev_b32_e32 v88, 2, v7
	v_lshl_add_u64 v[64:65], s[90:91], 0, v[4:5]
	v_cmp_eq_u32_e32 vcc, 0, v7
	v_lshl_add_u64 v[66:67], v[2:3], 2, s[2:3]
	v_add_u32_e32 v72, s7, v6
	v_lshl_add_u64 v[74:75], s[0:1], 0, v[96:97]
	v_readlane_b32 s7, v246, 8
	s_lshr_b32 s32, s7, 6
	s_and_b32 s7, s7, 7
	s_lshl_b32 s7, s7, 2
	s_add_i32 s7, s7, s32
	v_readlane_b32 s12, v249, 8
	v_readlane_b32 s13, v249, 9
	v_readlane_b32 s14, v249, 10
	v_readlane_b32 s15, v249, 11
	v_readlane_b32 s16, v249, 12
	v_readlane_b32 s17, v249, 13
	v_readlane_b32 s18, v249, 14
	v_readlane_b32 s19, v249, 15
	v_readlane_b32 s20, v249, 16
	v_readlane_b32 s21, v249, 17
	v_readlane_b32 s22, v249, 18
	v_readlane_b32 s23, v249, 19
	s_branch .LBB0_907

; template <int KSTEPS  >
; __device__ __forceinline__ void small_mma_ksplit(f32x4 (&acc)[2], const bf16_t* A, int lda, const bf16_t* Bt, int ldb, int n0, LAS unsigned char* lds, const SmallId& id) {
;     const int lane = id.fq * 16 + id.fr, k0 = id.w * (KSTEPS * 32);
;     f32x4 part[8][2];
; #pragma unroll
;     for (int rb = 0; rb < 8; ++rb) { part[rb][0] = (f32x4){0.f, 0.f, 0.f, 0.f}; part[rb][1] = part[rb][0]; }
;     const bf16_t* ap = A + (size_t)(MP + id.fr) * lda + k0 + 8 * id.fq;
;     const bf16_t* bp = Bt + (size_t)(n0 + id.fr) * ldb + k0 + 8 * id.fq;
; #pragma unroll 1
;     for (int ks = 0; ks < KSTEPS; ++ks) {
;         bf16x8 a[8], b[2];
; #pragma unroll
;         for (int rb = 0; rb < 8; ++rb) a[rb] = *(const bf16x8*)(ap + (size_t)(16 * rb) * lda + 32 * ks);
;         b[0] = *(const bf16x8*)(bp + 32 * ks); b[1] = *(const bf16x8*)(bp + (size_t)16 * ldb + 32 * ks);
; #pragma unroll
;         for (int rb = 0; rb < 8; ++rb) { part[rb][0] = __builtin_amdgcn_mfma_f32_16x16x32_bf16(b[0], a[rb], part[rb][0], 0, 0, 0); part[rb][1] = __builtin_amdgcn_mfma_f32_16x16x32_bf16(b[1], a[rb], part[rb][1], 0, 0, 0); }
;     }
;     LAS f32x4* red = (LAS f32x4*)lds;
; #pragma unroll
;     for (int rb = 0; rb < 8; ++rb) { red[((id.w * 8 + rb) * 2 + 0) * 64 + lane] = part[rb][0]; red[((id.w * 8 + rb) * 2 + 1) * 64 + lane] = part[rb][1]; }
;     asm volatile("s_waitcnt lgkmcnt(0)" ::: "memory"); __syncthreads();
;     acc[0] = (f32x4){0.f, 0.f, 0.f, 0.f}; acc[1] = acc[0];
; #pragma unroll
;     for (int w2 = 0; w2 < 8; ++w2) { acc[0] += red[((w2 * 8 + id.w) * 2 + 0) * 64 + lane]; acc[1] += red[((w2 * 8 + id.w) * 2 + 1) * 64 + lane]; }
;     asm volatile("s_waitcnt lgkmcnt(0)" ::: "memory"); __syncthreads();
; template <bool RES_F32, bool OUT_F32, int KSTEPS>
; __device__ __forceinline__ void small_res(const Params& p, LAS unsigned char* lds, const bf16_t* A, int lda, const bf16_t* Bt, int K, float* ssq_next, int G, int bx) {
;     ...
;         float s = 0.f;
; #pragma unroll
;         for (int nb = 0; nb < 2; ++nb) { const int col = n0 + 16 * nb + 4 * id.fq;
;             f32x4 r;
;             if (RES_F32) r = *(const f32x4*)(p.xs + (size_t)(id.row - MP) * DM + col);
;             else { const u32x2 w = *(const u32x2*)(XB + (size_t)id.row * DM + col); r = (f32x4){bf_lo(w.x), bf_hi(w.x), bf_lo(w.y), bf_hi(w.y)}; }
;             const f32x4 x = r + acc[nb];
.LBB0_908:
	s_waitcnt lgkmcnt(0)
	v_readlane_b32 s8, v246, 8
	v_readfirstlane_b32 s32, v222
	s_bfe_u32 s8, s8, 0x30003
	s_lshr_b32 s32, s32, 6
	s_cmp_eq_u32 s32, s8
	s_cselect_b32 s32, 1, 0
	s_lshl_b32 s9, s8, 11
	v_add_u32_e32 v70, s9, v78
	s_sub_i32 s9, s11, s10
	s_mul_i32 s8, s8, s9
	s_add_i32 s8, s8, s10
	s_mov_b32 s9, 0
	v_lshl_add_u64 v[72:73], v[74:75], 0, s[8:9]
	s_mov_b32 s8, s18
	v_lshl_add_u64 v[90:91], v[76:77], 0, s[8:9]
	s_mov_b32 s8, s19
	v_lshl_add_u64 v[92:93], v[76:77], 0, s[8:9]
	global_load_dwordx4 v[98:101], v[72:73], off
	global_load_dwordx4 v[102:105], v[90:91], off
	global_load_dwordx4 v[106:109], v[92:93], off
	global_load_dwordx4 v[110:113], v[72:73], off offset:64
	global_load_dwordx4 v[114:117], v[90:91], off offset:64
	global_load_dwordx4 v[118:121], v[92:93], off offset:64
	global_load_dwordx4 v[122:125], v[72:73], off offset:128
	global_load_dwordx4 v[126:129], v[90:91], off offset:128
	global_load_dwordx4 v[130:133], v[92:93], off offset:128
	global_load_dwordx4 v[134:137], v[72:73], off offset:192
	global_load_dwordx4 v[138:141], v[90:91], off offset:192
	global_load_dwordx4 v[142:145], v[92:93], off offset:192
	s_waitcnt vmcnt(9)
	v_mfma_f32_16x16x32_bf16 v[36:39], v[102:105], v[98:101], v[36:39]
	v_mfma_f32_16x16x32_bf16 v[24:27], v[106:109], v[98:101], v[24:27]
	s_waitcnt vmcnt(6)
	v_mfma_f32_16x16x32_bf16 v[36:39], v[114:117], v[110:113], v[36:39]
	v_mfma_f32_16x16x32_bf16 v[24:27], v[118:121], v[110:113], v[24:27]
	s_waitcnt vmcnt(3)
	v_mfma_f32_16x16x32_bf16 v[36:39], v[126:129], v[122:125], v[36:39]
	v_mfma_f32_16x16x32_bf16 v[24:27], v[130:133], v[122:125], v[24:27]
	s_waitcnt vmcnt(0)
	v_mfma_f32_16x16x32_bf16 v[36:39], v[138:141], v[134:137], v[36:39]
	v_mfma_f32_16x16x32_bf16 v[24:27], v[142:145], v[134:137], v[24:27]
	s_nop 7
	s_nop 1
	ds_write_b128 v70, v[36:39]
	ds_write_b128 v70, v[24:27] offset:1024
	s_waitcnt lgkmcnt(0)
	s_waitcnt lgkmcnt(0)
	s_barrier
	ds_read_b128 v[0:3], v79
	v_lshl_or_b32 v12, s7, 5, v88
	v_ashrrev_i32_e32 v13, 31, v12
	v_lshl_add_u64 v[14:15], v[12:13], 2, v[68:69]
	s_waitcnt lgkmcnt(0)
	v_pk_add_f32 v[4:5], v[2:3], 0 op_sel_hi:[1,0]
	v_pk_add_f32 v[6:7], v[0:1], 0 op_sel_hi:[1,0]
	ds_read_b128 v[0:3], v79 offset:1024
	s_waitcnt lgkmcnt(0)
	v_pk_add_f32 v[8:9], v[2:3], 0 op_sel_hi:[1,0]
	v_pk_add_f32 v[10:11], v[0:1], 0 op_sel_hi:[1,0]
	ds_read_b128 v[0:3], v79 offset:16384
	s_waitcnt lgkmcnt(0)
	v_pk_add_f32 v[4:5], v[4:5], v[2:3]
	v_pk_add_f32 v[6:7], v[6:7], v[0:1]
	ds_read_b128 v[0:3], v79 offset:17408
	s_waitcnt lgkmcnt(0)
	v_pk_add_f32 v[8:9], v[8:9], v[2:3]
	v_pk_add_f32 v[10:11], v[10:11], v[0:1]
	ds_read_b128 v[0:3], v79 offset:32768
	s_waitcnt lgkmcnt(0)
	v_pk_add_f32 v[4:5], v[4:5], v[2:3]
	v_pk_add_f32 v[6:7], v[6:7], v[0:1]
	ds_read_b128 v[0:3], v79 offset:33792
	s_waitcnt lgkmcnt(0)
	v_pk_add_f32 v[8:9], v[8:9], v[2:3]
	v_pk_add_f32 v[10:11], v[10:11], v[0:1]
	ds_read_b128 v[0:3], v79 offset:49152
	s_waitcnt lgkmcnt(0)
	v_pk_add_f32 v[4:5], v[4:5], v[2:3]
	v_pk_add_f32 v[6:7], v[6:7], v[0:1]
	ds_read_b128 v[0:3], v79 offset:50176
	s_waitcnt lgkmcnt(0)
	v_pk_add_f32 v[8:9], v[8:9], v[2:3]
	v_pk_add_f32 v[10:11], v[10:11], v[0:1]
	ds_read_b128 v[0:3], v80
	s_waitcnt lgkmcnt(0)
	v_pk_add_f32 v[4:5], v[4:5], v[2:3]
	v_pk_add_f32 v[6:7], v[6:7], v[0:1]
	ds_read_b128 v[0:3], v81
	s_waitcnt lgkmcnt(0)
	v_pk_add_f32 v[8:9], v[8:9], v[2:3]
	v_pk_add_f32 v[10:11], v[10:11], v[0:1]
	ds_read_b128 v[0:3], v82
	s_waitcnt lgkmcnt(0)
	v_pk_add_f32 v[4:5], v[4:5], v[2:3]
	v_pk_add_f32 v[6:7], v[6:7], v[0:1]
	ds_read_b128 v[0:3], v83
	s_waitcnt lgkmcnt(0)
	v_pk_add_f32 v[8:9], v[8:9], v[2:3]
	v_pk_add_f32 v[10:11], v[10:11], v[0:1]
	ds_read_b128 v[0:3], v84
	s_waitcnt lgkmcnt(0)
	v_pk_add_f32 v[4:5], v[4:5], v[2:3]
	v_pk_add_f32 v[6:7], v[6:7], v[0:1]
	ds_read_b128 v[0:3], v85
	s_waitcnt lgkmcnt(0)
	v_pk_add_f32 v[8:9], v[8:9], v[2:3]
	v_pk_add_f32 v[10:11], v[10:11], v[0:1]
	ds_read_b128 v[0:3], v86
	s_waitcnt lgkmcnt(0)
	v_pk_add_f32 v[4:5], v[4:5], v[2:3]
	v_pk_add_f32 v[6:7], v[6:7], v[0:1]
	ds_read_b128 v[0:3], v87
	s_waitcnt lgkmcnt(0)
	s_waitcnt lgkmcnt(0)
	s_barrier
	s_mul_i32 exec_lo, s32, -1
	s_mov_b32 exec_hi, exec_lo
	v_pk_add_f32 v[8:9], v[8:9], v[2:3]
	v_pk_add_f32 v[10:11], v[10:11], v[0:1]
	global_load_dwordx4 v[0:3], v[14:15], off
	s_waitcnt vmcnt(0)
	v_pk_add_f32 v[0:1], v[6:7], v[0:1]
	v_pk_add_f32 v[2:3], v[4:5], v[2:3]
	v_cvt_pk_bf16_f32 v4, v0, v1
	v_mul_f32_e32 v1, v1, v1
	v_lshl_add_u64 v[6:7], v[12:13], 1, v[64:65]
	v_fmac_f32_e32 v1, v0, v0
	v_mul_f32_e32 v0, v3, v3
	v_cvt_pk_bf16_f32 v5, v2, v3
	global_store_dwordx2 v[6:7], v[4:5], off
	v_fmac_f32_e32 v0, v2, v2
	v_add_f32_e32 v12, v1, v0
	global_load_dwordx4 v[0:3], v[14:15], off offset:64
	s_waitcnt vmcnt(0)
	v_pk_add_f32 v[0:1], v[10:11], v[0:1]
	v_pk_add_f32 v[2:3], v[8:9], v[2:3]
	v_cvt_pk_bf16_f32 v4, v0, v1
	v_mul_f32_e32 v1, v1, v1
	v_fmac_f32_e32 v1, v0, v0
	v_mul_f32_e32 v0, v3, v3
	v_cvt_pk_bf16_f32 v5, v2, v3
	v_fmac_f32_e32 v0, v2, v2
	v_and_b32_e32 v2, 64, v225
	v_add_f32_e32 v0, v1, v0
	v_xor_b32_e32 v1, 16, v225
	v_add_u32_e32 v2, 64, v2
	v_cmp_lt_i32_e64 s[0:1], v1, v2
	v_add_f32_e32 v0, v12, v0
	global_store_dwordx2 v[6:7], v[4:5], off offset:32
	v_cndmask_b32_e64 v1, v225, v1, s[0:1]
	v_lshlrev_b32_e32 v1, 2, v1
	ds_bpermute_b32 v1, v1, v0
	s_waitcnt lgkmcnt(0)
	v_add_f32_e32 v0, v0, v1
	v_xor_b32_e32 v1, 32, v225
	v_cmp_lt_i32_e64 s[0:1], v1, v2
	s_nop 1
	v_cndmask_b32_e64 v1, v225, v1, s[0:1]
	v_lshlrev_b32_e32 v1, 2, v1
	ds_bpermute_b32 v1, v1, v0
	s_and_saveexec_b64 s[0:1], vcc
	s_cbranch_execz .LBB0_906
	s_waitcnt lgkmcnt(0)
	v_add_f32_e32 v0, v0, v1
	global_atomic_add_f32 v[66:67], v0, off
	s_branch .LBB0_906

; #define LAS __attribute__((address_space(3)))
; __device__ __forceinline__ SmallId small_id() { int tid = threadIdx.x; asm volatile("" : "+v"(tid)); SmallId i; i.w = __builtin_amdgcn_readfirstlane(tid >> 6); i.fr = tid & 15; i.fq = (tid & 63) >> 4; i.row = MP + 16 * i.w + i.fr; return i; }
; template <int KSTEPS  >
; __device__ __forceinline__ void small_mma_ksplit(f32x4 (&acc)[2], const bf16_t* A, int lda, const bf16_t* Bt, int ldb, int n0, LAS unsigned char* lds, const SmallId& id) {
;     const int lane = id.fq * 16 + id.fr, k0 = id.w * (KSTEPS * 32);
;     f32x4 part[8][2];
; #pragma unroll
;     for (int rb = 0; rb < 8; ++rb) { part[rb][0] = (f32x4){0.f, 0.f, 0.f, 0.f}; part[rb][1] = part[rb][0]; }
;     const bf16_t* ap = A + (size_t)(MP + id.fr) * lda + k0 + 8 * id.fq;
;     const bf16_t* bp = Bt + (size_t)(n0 + id.fr) * ldb + k0 + 8 * id.fq;
; template <bool RES_F32, bool OUT_F32, int KSTEPS>
; __device__ __forceinline__ void small_res(const Params& p, LAS unsigned char* lds, const bf16_t* A, int lda, const bf16_t* Bt, int K, float* ssq_next, int G, int bx) {
;     const SmallId id = small_id();
;     bf16_t* XB = (bf16_t*)(p.ws + WS_XB);
;     for (int ts = G - 1 - bx; ts < DM / 32; ts += G) {
;         const int n0 = ts * 32; f32x4 acc[2] = {(f32x4){0.f, 0.f, 0.f, 0.f}, (f32x4){0.f, 0.f, 0.f, 0.f}};
;         small_mma_ksplit<KSTEPS>(acc, A, lda, Bt, K, n0, lds, id);
;         float s = 0.f;
; #pragma unroll
;         for (int nb = 0; nb < 2; ++nb) { const int col = n0 + 16 * nb + 4 * id.fq;
.LBB0_1219:
	v_readlane_b32 s0, v246, 16
	s_waitcnt vmcnt(0)
	v_readlane_b32 s2, v246, 13
	s_add_u32 s22, s0, 0x1580000
	v_readlane_b32 s0, v246, 17
	v_readlane_b32 s3, v246, 14
	v_readlane_b32 s54, v248, 44
	s_addc_u32 s23, s0, 0
	s_mov_b64 s[0:1], -1
	s_and_b64 vcc, exec, s[2:3]
	v_readlane_b32 s81, v246, 8
	v_readlane_b32 s92, v246, 9
	v_readlane_b32 s55, v248, 45
	s_mov_b32 s52, 0x1ab00000
	s_mov_b32 s53, 0x1ab16000
	s_mov_b32 s56, 0x1ab2c000
	s_mov_b32 s57, 0x1ab42000
	s_mov_b32 s58, 0x1ab58000
	s_mov_b32 s59, 0x1ab6e000
	s_mov_b32 s60, 0x1ab84000
	s_mov_b32 s61, 0x1ab9a000
	s_mov_b32 s62, 0x1680000
	s_mov_b32 s63, 0x1696000
	s_waitcnt lgkmcnt(0)
	s_barrier
	v_readlane_b32 s93, v246, 10
	s_cbranch_vccz .LBB0_1250
	v_readlane_b32 s0, v246, 22
	v_mov_b32_e32 v0, v222
	v_readlane_b32 s1, v246, 23
	v_readlane_b32 s64, v246, 11
	s_and_b64 vcc, exec, s[0:1]
	v_readfirstlane_b32 s0, v0
	v_readlane_b32 s65, v246, 12
	s_ashr_i32 s2, s0, 6
	s_lshl_b32 s0, s2, 4
	v_and_b32_e32 v4, 15, v0
	s_add_i32 s0, s0, 0x8000
	v_or_b32_e32 v2, s0, v4
	v_bfe_u32 v5, v0, 4, 2
	s_mul_i32 s0, s2, 0x160
	s_lshl_b32 s3, s2, 14
	v_lshlrev_b32_e32 v0, 4, v0
	s_lshl_b32 s2, s2, 11
	s_add_i32 s3, s3, 0
	v_and_b32_e32 v0, 0x3f0, v0
	s_add_i32 s2, s2, 0
	v_add_u32_e32 v74, s3, v0
	s_add_i32 s3, s2, 0x10400
	s_ashr_i32 s1, s0, 31
	v_add_u32_e32 v77, s3, v0
	s_add_i32 s3, s2, 0x14400
	v_add_u32_e32 v75, s2, v0
	v_add_u32_e32 v79, s3, v0
	s_add_i32 s3, s2, 0x18400
	s_add_i32 s2, s2, 0x1c400
	s_lshl_b64 s[0:1], s[0:1], 1
	v_add_u32_e32 v83, s2, v0
	v_ashrrev_i32_e32 v3, 31, v2
	s_add_u32 s2, s86, s0
	v_add_u32_e32 v81, s3, v0
	v_lshlrev_b64 v[0:1], 11, v[2:3]
	s_addc_u32 s3, s87, s1
	v_readlane_b32 s7, v246, 15
	v_lshl_add_u64 v[64:65], s[90:91], 0, v[0:1]
	v_lshlrev_b64 v[0:1], 12, v[2:3]
	s_add_u32 s2, s2, s7
	v_lshl_add_u64 v[66:67], s[64:65], 0, v[0:1]
	v_lshlrev_b32_e32 v0, 4, v5
	v_mov_b32_e32 v1, v97
	s_addc_u32 s3, s3, 0
	v_mul_u32_u24_e32 v96, 0x1600, v4
	v_lshl_add_u64 v[68:69], s[2:3], 0, v[0:1]
	v_or_b32_e32 v0, s0, v0
	v_mov_b32_e32 v1, s1
	v_readlane_b32 s2, v246, 8
	s_lshr_b32 s32, s2, 6
	s_and_b32 s2, s2, 7
	s_lshl_b32 s2, s2, 2
	s_add_i32 s2, s2, s32
	s_lshl_b32 s2, s2, 5
	v_lshl_add_u64 v[0:1], v[0:1], 0, v[96:97]
	v_add_u32_e32 v76, 0x10000, v75
	v_add_u32_e32 v78, 0x14000, v75
	v_add_u32_e32 v80, 0x18000, v75
	v_add_u32_e32 v82, 0x1c000, v75
	v_lshlrev_b32_e32 v84, 2, v5
	v_add_u32_e32 v85, s2, v4
	v_lshl_add_u64 v[70:71], s[86:87], 0, v[0:1]
	v_readlane_b32 s2, v246, 8
	s_lshr_b32 s32, s2, 6
	s_and_b32 s2, s2, 7
	s_lshl_b32 s2, s2, 2
	s_add_i32 s2, s2, s32

; #define LAS __attribute__((address_space(3)))
; template <int KSTEPS  >
; __device__ __forceinline__ void small_mma_ksplit(f32x4 (&acc)[2], const bf16_t* A, int lda, const bf16_t* Bt, int ldb, int n0, LAS unsigned char* lds, const SmallId& id) {
;     const int lane = id.fq * 16 + id.fr, k0 = id.w * (KSTEPS * 32);
;     f32x4 part[8][2];
; #pragma unroll
;     for (int rb = 0; rb < 8; ++rb) { part[rb][0] = (f32x4){0.f, 0.f, 0.f, 0.f}; part[rb][1] = part[rb][0]; }
;     const bf16_t* ap = A + (size_t)(MP + id.fr) * lda + k0 + 8 * id.fq;
;     const bf16_t* bp = Bt + (size_t)(n0 + id.fr) * ldb + k0 + 8 * id.fq;
; #pragma unroll 1
;     for (int ks = 0; ks < KSTEPS; ++ks) {
;         bf16x8 a[8], b[2];
; #pragma unroll
;         for (int rb = 0; rb < 8; ++rb) a[rb] = *(const bf16x8*)(ap + (size_t)(16 * rb) * lda + 32 * ks);
;         b[0] = *(const bf16x8*)(bp + 32 * ks); b[1] = *(const bf16x8*)(bp + (size_t)16 * ldb + 32 * ks);
; #pragma unroll
;         for (int rb = 0; rb < 8; ++rb) { part[rb][0] = __builtin_amdgcn_mfma_f32_16x16x32_bf16(b[0], a[rb], part[rb][0], 0, 0, 0); part[rb][1] = __builtin_amdgcn_mfma_f32_16x16x32_bf16(b[1], a[rb], part[rb][1], 0, 0, 0); }
;     }
;     LAS f32x4* red = (LAS f32x4*)lds;
; #pragma unroll
;     for (int rb = 0; rb < 8; ++rb) { red[((id.w * 8 + rb) * 2 + 0) * 64 + lane] = part[rb][0]; red[((id.w * 8 + rb) * 2 + 1) * 64 + lane] = part[rb][1]; }
;     asm volatile("s_waitcnt lgkmcnt(0)" ::: "memory"); __syncthreads();
;     acc[0] = (f32x4){0.f, 0.f, 0.f, 0.f}; acc[1] = acc[0];
; #pragma unroll
;     for (int w2 = 0; w2 < 8; ++w2) { acc[0] += red[((w2 * 8 + id.w) * 2 + 0) * 64 + lane]; acc[1] += red[((w2 * 8 + id.w) * 2 + 1) * 64 + lane]; }
;     asm volatile("s_waitcnt lgkmcnt(0)" ::: "memory"); __syncthreads();
.LBB0_1223:
	s_waitcnt lgkmcnt(0)
	v_readlane_b32 s0, v246, 8
	v_readfirstlane_b32 s32, v222
	s_bfe_u32 s0, s0, 0x30003
	s_lshr_b32 s32, s32, 6
	s_cmp_eq_u32 s32, s0
	s_cselect_b32 s32, 1, 0
	s_lshl_b32 s1, s0, 11
	v_add_u32_e32 v68, s1, v74
	s_sub_i32 s1, s53, s52
	s_mul_i32 s0, s0, s1
	s_add_i32 s0, s0, s52
	s_mov_b32 s1, 0
	v_lshl_add_u64 v[86:87], v[70:71], 0, s[0:1]
	s_mov_b32 s0, s62
	v_lshl_add_u64 v[88:89], v[72:73], 0, s[0:1]
	s_mov_b32 s0, s63
	v_lshl_add_u64 v[90:91], v[72:73], 0, s[0:1]
	global_load_dwordx4 v[92:95], v[86:87], off
	global_load_dwordx4 v[98:101], v[88:89], off
	global_load_dwordx4 v[102:105], v[90:91], off
	global_load_dwordx4 v[106:109], v[86:87], off offset:64
	global_load_dwordx4 v[110:113], v[88:89], off offset:64
	global_load_dwordx4 v[114:117], v[90:91], off offset:64
	global_load_dwordx4 v[118:121], v[86:87], off offset:128
	global_load_dwordx4 v[122:125], v[88:89], off offset:128
	global_load_dwordx4 v[126:129], v[90:91], off offset:128
	global_load_dwordx4 v[130:133], v[86:87], off offset:192
	global_load_dwordx4 v[134:137], v[88:89], off offset:192
	global_load_dwordx4 v[138:141], v[90:91], off offset:192
	global_load_dwordx4 v[142:145], v[86:87], off offset:256
	global_load_dwordx4 v[146:149], v[88:89], off offset:256
	global_load_dwordx4 v[150:153], v[90:91], off offset:256
	global_load_dwordx4 v[154:157], v[86:87], off offset:320
	global_load_dwordx4 v[158:161], v[88:89], off offset:320
	global_load_dwordx4 v[162:165], v[90:91], off offset:320
	global_load_dwordx4 v[166:169], v[86:87], off offset:384
	global_load_dwordx4 v[170:173], v[88:89], off offset:384
	global_load_dwordx4 v[174:177], v[90:91], off offset:384
	global_load_dwordx4 v[178:181], v[86:87], off offset:448
	global_load_dwordx4 v[182:185], v[88:89], off offset:448
	global_load_dwordx4 v[186:189], v[90:91], off offset:448
	s_waitcnt vmcnt(21)
	v_mfma_f32_16x16x32_bf16 v[36:39], v[98:101], v[92:95], v[36:39]
	v_mfma_f32_16x16x32_bf16 v[24:27], v[102:105], v[92:95], v[24:27]
	global_load_dwordx4 v[92:95], v[86:87], off offset:512
	global_load_dwordx4 v[98:101], v[88:89], off offset:512
	global_load_dwordx4 v[102:105], v[90:91], off offset:512
	s_waitcnt vmcnt(21)
	v_mfma_f32_16x16x32_bf16 v[36:39], v[110:113], v[106:109], v[36:39]
	v_mfma_f32_16x16x32_bf16 v[24:27], v[114:117], v[106:109], v[24:27]
	global_load_dwordx4 v[106:109], v[86:87], off offset:576
	global_load_dwordx4 v[110:113], v[88:89], off offset:576
	global_load_dwordx4 v[114:117], v[90:91], off offset:576
	s_waitcnt vmcnt(21)
	v_mfma_f32_16x16x32_bf16 v[36:39], v[122:125], v[118:121], v[36:39]
	v_mfma_f32_16x16x32_bf16 v[24:27], v[126:129], v[118:121], v[24:27]
	global_load_dwordx4 v[118:121], v[86:87], off offset:640
	global_load_dwordx4 v[122:125], v[88:89], off offset:640
	global_load_dwordx4 v[126:129], v[90:91], off offset:640
	s_waitcnt vmcnt(21)
	v_mfma_f32_16x16x32_bf16 v[36:39], v[134:137], v[130:133], v[36:39]
	v_mfma_f32_16x16x32_bf16 v[24:27], v[138:141], v[130:133], v[24:27]
	s_waitcnt vmcnt(18)
	v_mfma_f32_16x16x32_bf16 v[36:39], v[146:149], v[142:145], v[36:39]
	v_mfma_f32_16x16x32_bf16 v[24:27], v[150:153], v[142:145], v[24:27]
	s_waitcnt vmcnt(15)
	v_mfma_f32_16x16x32_bf16 v[36:39], v[158:161], v[154:157], v[36:39]
	v_mfma_f32_16x16x32_bf16 v[24:27], v[162:165], v[154:157], v[24:27]
	s_waitcnt vmcnt(12)
	v_mfma_f32_16x16x32_bf16 v[36:39], v[170:173], v[166:169], v[36:39]
	v_mfma_f32_16x16x32_bf16 v[24:27], v[174:177], v[166:169], v[24:27]
	s_waitcnt vmcnt(9)
	v_mfma_f32_16x16x32_bf16 v[36:39], v[182:185], v[178:181], v[36:39]
	v_mfma_f32_16x16x32_bf16 v[24:27], v[186:189], v[178:181], v[24:27]
	s_waitcnt vmcnt(6)
	v_mfma_f32_16x16x32_bf16 v[36:39], v[98:101], v[92:95], v[36:39]
	v_mfma_f32_16x16x32_bf16 v[24:27], v[102:105], v[92:95], v[24:27]
	s_waitcnt vmcnt(3)
	v_mfma_f32_16x16x32_bf16 v[36:39], v[110:113], v[106:109], v[36:39]
	v_mfma_f32_16x16x32_bf16 v[24:27], v[114:117], v[106:109], v[24:27]
	s_waitcnt vmcnt(0)
	v_mfma_f32_16x16x32_bf16 v[36:39], v[122:125], v[118:121], v[36:39]
	v_mfma_f32_16x16x32_bf16 v[24:27], v[126:129], v[118:121], v[24:27]
	s_nop 7
	s_nop 1
	ds_write_b128 v68, v[36:39]
	ds_write_b128 v68, v[24:27] offset:1024
	s_waitcnt lgkmcnt(0)
	s_waitcnt lgkmcnt(0)
	s_barrier
; __device__ __forceinline__ unsigned cvt_pk_bf16(float lo, float hi) { unsigned r; asm volatile("v_cvt_pk_bf16_f32 %0, %1, %2" : "=v"(r) : "v"(lo), "v"(hi)); return r; }
; template <int KSTEPS  >
; __device__ __forceinline__ void small_mma_ksplit(f32x4 (&acc)[2], const bf16_t* A, int lda, const bf16_t* Bt, int ldb, int n0, LAS unsigned char* lds, const SmallId& id) {
;     ...
;     acc[0] = (f32x4){0.f, 0.f, 0.f, 0.f}; acc[1] = acc[0];
; #pragma unroll
;     for (int w2 = 0; w2 < 8; ++w2) { acc[0] += red[((w2 * 8 + id.w) * 2 + 0) * 64 + lane]; acc[1] += red[((w2 * 8 + id.w) * 2 + 1) * 64 + lane]; }
;     asm volatile("s_waitcnt lgkmcnt(0)" ::: "memory"); __syncthreads();
; template <bool RES_F32, bool OUT_F32, int KSTEPS>
; __device__ __forceinline__ void small_res(const Params& p, LAS unsigned char* lds, const bf16_t* A, int lda, const bf16_t* Bt, int K, float* ssq_next, int G, int bx) {
;     ...
;         float s = 0.f;
; #pragma unroll
;         for (int nb = 0; nb < 2; ++nb) { const int col = n0 + 16 * nb + 4 * id.fq;
;             f32x4 r;
;             if (RES_F32) r = *(const f32x4*)(p.xs + (size_t)(id.row - MP) * DM + col);
;             else { const u32x2 w = *(const u32x2*)(XB + (size_t)id.row * DM + col); r = (f32x4){bf_lo(w.x), bf_hi(w.x), bf_lo(w.y), bf_hi(w.y)}; }
;             const f32x4 x = r + acc[nb];
;             if (OUT_F32) *(f32x4*)(p.out + (size_t)id.row * DM + col) = x;
;             else { u32x2 w; w.x = cvt_pk_bf16(x[0], x[1]); w.y = cvt_pk_bf16(x[2], x[3]); *(u32x2*)(XB + (size_t)id.row * DM + col) = w; }
;             s += (x[0] * x[0] + x[1] * x[1]) + (x[2] * x[2] + x[3] * x[3]); }
;         if (!OUT_F32) { s += __shfl_xor(s, 16); s += __shfl_xor(s, 32); if (id.fq == 0) atomicAdd(ssq_next + id.row, s); }
;     }
	ds_read_b128 v[0:3], v75
	v_lshl_or_b32 v12, s2, 5, v84
	v_ashrrev_i32_e32 v13, 31, v12
	v_lshl_add_u64 v[14:15], v[12:13], 1, v[64:65]
	s_add_i32 s2, s2, s92
	s_waitcnt lgkmcnt(0)
	v_pk_add_f32 v[4:5], v[2:3], 0 op_sel_hi:[1,0]
	v_pk_add_f32 v[6:7], v[0:1], 0 op_sel_hi:[1,0]
	ds_read_b128 v[0:3], v75 offset:1024
	v_add_u32_e32 v85, s37, v85
	s_cmp_lt_i32 s2, 32
	s_waitcnt lgkmcnt(0)
	v_pk_add_f32 v[8:9], v[2:3], 0 op_sel_hi:[1,0]
	v_pk_add_f32 v[10:11], v[0:1], 0 op_sel_hi:[1,0]
	ds_read_b128 v[0:3], v75 offset:16384
	s_waitcnt lgkmcnt(0)
	v_pk_add_f32 v[4:5], v[4:5], v[2:3]
	v_pk_add_f32 v[6:7], v[6:7], v[0:1]
	ds_read_b128 v[0:3], v75 offset:17408
	s_waitcnt lgkmcnt(0)
	v_pk_add_f32 v[8:9], v[8:9], v[2:3]
	v_pk_add_f32 v[10:11], v[10:11], v[0:1]
	ds_read_b128 v[0:3], v75 offset:32768
	s_waitcnt lgkmcnt(0)
	v_pk_add_f32 v[4:5], v[4:5], v[2:3]
	v_pk_add_f32 v[6:7], v[6:7], v[0:1]
	ds_read_b128 v[0:3], v75 offset:33792
	s_waitcnt lgkmcnt(0)
	v_pk_add_f32 v[8:9], v[8:9], v[2:3]
	v_pk_add_f32 v[10:11], v[10:11], v[0:1]
	ds_read_b128 v[0:3], v75 offset:49152
	s_waitcnt lgkmcnt(0)
	v_pk_add_f32 v[4:5], v[4:5], v[2:3]
	v_pk_add_f32 v[6:7], v[6:7], v[0:1]
	ds_read_b128 v[0:3], v75 offset:50176
	s_waitcnt lgkmcnt(0)
	v_pk_add_f32 v[8:9], v[8:9], v[2:3]
	v_pk_add_f32 v[10:11], v[10:11], v[0:1]
	ds_read_b128 v[0:3], v76
	s_waitcnt lgkmcnt(0)
	v_pk_add_f32 v[4:5], v[4:5], v[2:3]
	v_pk_add_f32 v[6:7], v[6:7], v[0:1]
	ds_read_b128 v[0:3], v77
	s_waitcnt lgkmcnt(0)
	v_pk_add_f32 v[8:9], v[8:9], v[2:3]
	v_pk_add_f32 v[10:11], v[10:11], v[0:1]
	ds_read_b128 v[0:3], v78
	s_waitcnt lgkmcnt(0)
	v_pk_add_f32 v[4:5], v[4:5], v[2:3]
	v_pk_add_f32 v[6:7], v[6:7], v[0:1]
	ds_read_b128 v[0:3], v79
	s_waitcnt lgkmcnt(0)
	v_pk_add_f32 v[8:9], v[8:9], v[2:3]
	v_pk_add_f32 v[10:11], v[10:11], v[0:1]
	ds_read_b128 v[0:3], v80
	s_waitcnt lgkmcnt(0)
	v_pk_add_f32 v[4:5], v[4:5], v[2:3]
	v_pk_add_f32 v[6:7], v[6:7], v[0:1]
	ds_read_b128 v[0:3], v81
	s_waitcnt lgkmcnt(0)
	v_pk_add_f32 v[8:9], v[8:9], v[2:3]
	v_pk_add_f32 v[10:11], v[10:11], v[0:1]
	ds_read_b128 v[0:3], v82
	s_waitcnt lgkmcnt(0)
	v_pk_add_f32 v[4:5], v[4:5], v[2:3]
	v_pk_add_f32 v[6:7], v[6:7], v[0:1]
	ds_read_b128 v[0:3], v83
	s_waitcnt lgkmcnt(0)
	s_waitcnt lgkmcnt(0)
	s_barrier
	s_mul_i32 exec_lo, s32, -1
	s_mov_b32 exec_hi, exec_lo
	v_pk_add_f32 v[10:11], v[10:11], v[0:1]
	global_load_dwordx2 v[0:1], v[14:15], off
	v_pk_add_f32 v[8:9], v[8:9], v[2:3]
	s_waitcnt vmcnt(0) lgkmcnt(0)
	v_lshlrev_b32_e32 v2, 16, v0
	v_and_b32_e32 v3, 0xffff0000, v0
	v_lshlrev_b32_e32 v16, 16, v1
	v_and_b32_e32 v17, 0xffff0000, v1
	v_pk_add_f32 v[0:1], v[6:7], v[2:3]
	v_pk_add_f32 v[2:3], v[4:5], v[16:17]
	v_lshl_add_u64 v[4:5], v[12:13], 2, v[66:67]
	global_store_dwordx4 v[4:5], v[0:3], off
	global_load_dwordx2 v[0:1], v[14:15], off offset:32
	s_waitcnt vmcnt(0) lgkmcnt(0)
	v_lshlrev_b32_e32 v6, 16, v0
	v_and_b32_e32 v7, 0xffff0000, v0
	v_lshlrev_b32_e32 v0, 16, v1
	v_and_b32_e32 v1, 0xffff0000, v1
	v_pk_add_f32 v[2:3], v[8:9], v[0:1]
	v_pk_add_f32 v[0:1], v[10:11], v[6:7]
	global_store_dwordx4 v[4:5], v[0:3], off offset:64
	s_cbranch_scc1 .LBB0_1222

; #define LAS __attribute__((address_space(3)))
; __device__ __forceinline__ SmallId small_id() { int tid = threadIdx.x; asm volatile("" : "+v"(tid)); SmallId i; i.w = __builtin_amdgcn_readfirstlane(tid >> 6); i.fr = tid & 15; i.fq = (tid & 63) >> 4; i.row = MP + 16 * i.w + i.fr; return i; }
; template <int KSTEPS  >
; __device__ __forceinline__ void small_mma_ksplit(f32x4 (&acc)[2], const bf16_t* A, int lda, const bf16_t* Bt, int ldb, int n0, LAS unsigned char* lds, const SmallId& id) {
;     const int lane = id.fq * 16 + id.fr, k0 = id.w * (KSTEPS * 32);
;     f32x4 part[8][2];
; #pragma unroll
;     for (int rb = 0; rb < 8; ++rb) { part[rb][0] = (f32x4){0.f, 0.f, 0.f, 0.f}; part[rb][1] = part[rb][0]; }
;     const bf16_t* ap = A + (size_t)(MP + id.fr) * lda + k0 + 8 * id.fq;
;     const bf16_t* bp = Bt + (size_t)(n0 + id.fr) * ldb + k0 + 8 * id.fq;
; template <bool RES_F32, bool OUT_F32, int KSTEPS>
; __device__ __forceinline__ void small_res(const Params& p, LAS unsigned char* lds, const bf16_t* A, int lda, const bf16_t* Bt, int K, float* ssq_next, int G, int bx) {
;     const SmallId id = small_id();
;     bf16_t* XB = (bf16_t*)(p.ws + WS_XB);
;     for (int ts = G - 1 - bx; ts < DM / 32; ts += G) {
;         const int n0 = ts * 32; f32x4 acc[2] = {(f32x4){0.f, 0.f, 0.f, 0.f}, (f32x4){0.f, 0.f, 0.f, 0.f}};
;         small_mma_ksplit<KSTEPS>(acc, A, lda, Bt, K, n0, lds, id);
;         float s = 0.f;
; #pragma unroll
;         for (int nb = 0; nb < 2; ++nb) { const int col = n0 + 16 * nb + 4 * id.fq;
.LBB0_1250:
	s_and_b64 vcc, exec, s[0:1]
	s_cbranch_vccz .LBB0_1298
	v_readlane_b32 s0, v246, 22
	s_add_u32 s2, s86, 0x40800
	v_mov_b32_e32 v0, v222
	v_readlane_b32 s1, v246, 23
	s_addc_u32 s3, s87, 0
	s_and_b64 vcc, exec, s[0:1]
	v_readfirstlane_b32 s0, v0
	s_ashr_i32 s7, s0, 6
	s_lshl_b32 s0, s7, 4
	v_and_b32_e32 v4, 15, v0
	s_add_i32 s0, s0, 0x8000
	v_or_b32_e32 v2, s0, v4
	v_bfe_u32 v5, v0, 4, 2
	s_mul_i32 s0, s7, 0x160
	s_lshl_b32 s8, s7, 14
	v_lshlrev_b32_e32 v0, 4, v0
	s_lshl_b32 s7, s7, 11
	s_add_i32 s8, s8, 0
	v_and_b32_e32 v0, 0x3f0, v0
	s_add_i32 s7, s7, 0
	v_add_u32_e32 v74, s8, v0
	s_add_i32 s8, s7, 0x10400
	s_ashr_i32 s1, s0, 31
	v_add_u32_e32 v77, s8, v0
	s_add_i32 s8, s7, 0x14400
	v_add_u32_e32 v75, s7, v0
	v_add_u32_e32 v79, s8, v0
	s_add_i32 s8, s7, 0x18400
	s_add_i32 s7, s7, 0x1c400
	s_lshl_b64 s[0:1], s[0:1], 1
	v_add_u32_e32 v83, s7, v0
	s_add_u32 s7, s86, s0
	v_add_u32_e32 v81, s8, v0
	v_ashrrev_i32_e32 v3, 31, v2
	s_addc_u32 s9, s87, s1
	v_readlane_b32 s8, v246, 15
	v_lshlrev_b64 v[0:1], 11, v[2:3]
	s_add_u32 s8, s7, s8
	v_lshl_add_u64 v[64:65], s[90:91], 0, v[0:1]
	v_lshlrev_b32_e32 v0, 4, v5
	v_mov_b32_e32 v1, v97
	s_addc_u32 s9, s9, 0
	v_mul_u32_u24_e32 v96, 0x1600, v4
	v_lshl_add_u64 v[68:69], s[8:9], 0, v[0:1]
	v_or_b32_e32 v0, s0, v0
	v_mov_b32_e32 v1, s1
	v_readlane_b32 s7, v246, 8
	s_lshr_b32 s32, s7, 6
	s_and_b32 s7, s7, 7
	s_lshl_b32 s7, s7, 2
	s_add_i32 s7, s7, s32
	s_lshl_b32 s7, s7, 5
	v_lshl_add_u64 v[0:1], v[0:1], 0, v[96:97]
	v_add_u32_e32 v76, 0x10000, v75
	v_add_u32_e32 v78, 0x14000, v75
	v_add_u32_e32 v80, 0x18000, v75
	v_add_u32_e32 v82, 0x1c000, v75
	v_lshlrev_b32_e32 v84, 2, v5
	v_cmp_eq_u32_e32 vcc, 0, v5
	v_lshl_add_u64 v[66:67], v[2:3], 2, s[2:3]
	v_add_u32_e32 v85, s7, v4
	v_lshl_add_u64 v[70:71], s[86:87], 0, v[0:1]
	v_readlane_b32 s7, v246, 8
	s_lshr_b32 s32, s7, 6
	s_and_b32 s7, s7, 7
	s_lshl_b32 s7, s7, 2
	s_add_i32 s7, s7, s32
	s_branch .LBB0_1254

; #define LAS __attribute__((address_space(3)))
; template <int KSTEPS  >
; __device__ __forceinline__ void small_mma_ksplit(f32x4 (&acc)[2], const bf16_t* A, int lda, const bf16_t* Bt, int ldb, int n0, LAS unsigned char* lds, const SmallId& id) {
;     const int lane = id.fq * 16 + id.fr, k0 = id.w * (KSTEPS * 32);
;     f32x4 part[8][2];
; #pragma unroll
;     for (int rb = 0; rb < 8; ++rb) { part[rb][0] = (f32x4){0.f, 0.f, 0.f, 0.f}; part[rb][1] = part[rb][0]; }
;     const bf16_t* ap = A + (size_t)(MP + id.fr) * lda + k0 + 8 * id.fq;
;     const bf16_t* bp = Bt + (size_t)(n0 + id.fr) * ldb + k0 + 8 * id.fq;
; #pragma unroll 1
;     for (int ks = 0; ks < KSTEPS; ++ks) {
;         bf16x8 a[8], b[2];
; #pragma unroll
;         for (int rb = 0; rb < 8; ++rb) a[rb] = *(const bf16x8*)(ap + (size_t)(16 * rb) * lda + 32 * ks);
;         b[0] = *(const bf16x8*)(bp + 32 * ks); b[1] = *(const bf16x8*)(bp + (size_t)16 * ldb + 32 * ks);
; #pragma unroll
;         for (int rb = 0; rb < 8; ++rb) { part[rb][0] = __builtin_amdgcn_mfma_f32_16x16x32_bf16(b[0], a[rb], part[rb][0], 0, 0, 0); part[rb][1] = __builtin_amdgcn_mfma_f32_16x16x32_bf16(b[1], a[rb], part[rb][1], 0, 0, 0); }
;     }
;     LAS f32x4* red = (LAS f32x4*)lds;
; #pragma unroll
;     for (int rb = 0; rb < 8; ++rb) { red[((id.w * 8 + rb) * 2 + 0) * 64 + lane] = part[rb][0]; red[((id.w * 8 + rb) * 2 + 1) * 64 + lane] = part[rb][1]; }
;     asm volatile("s_waitcnt lgkmcnt(0)" ::: "memory"); __syncthreads();
;     acc[0] = (f32x4){0.f, 0.f, 0.f, 0.f}; acc[1] = acc[0];
; #pragma unroll
;     for (int w2 = 0; w2 < 8; ++w2) { acc[0] += red[((w2 * 8 + id.w) * 2 + 0) * 64 + lane]; acc[1] += red[((w2 * 8 + id.w) * 2 + 1) * 64 + lane]; }
;     asm volatile("s_waitcnt lgkmcnt(0)" ::: "memory"); __syncthreads();
.LBB0_1255:
	s_waitcnt lgkmcnt(0)
	v_readlane_b32 s8, v246, 8
	v_readfirstlane_b32 s32, v222
	s_bfe_u32 s8, s8, 0x30003
	s_lshr_b32 s32, s32, 6
	s_cmp_eq_u32 s32, s8
	s_cselect_b32 s32, 1, 0
	s_lshl_b32 s9, s8, 11
	v_add_u32_e32 v68, s9, v74
	s_sub_i32 s9, s53, s52
	s_mul_i32 s8, s8, s9
	s_add_i32 s8, s8, s52
	s_mov_b32 s9, 0
	v_lshl_add_u64 v[86:87], v[70:71], 0, s[8:9]
	s_mov_b32 s8, s62
	v_lshl_add_u64 v[88:89], v[72:73], 0, s[8:9]
	s_mov_b32 s8, s63
	v_lshl_add_u64 v[90:91], v[72:73], 0, s[8:9]
	global_load_dwordx4 v[92:95], v[86:87], off
	global_load_dwordx4 v[98:101], v[88:89], off
	global_load_dwordx4 v[102:105], v[90:91], off
	global_load_dwordx4 v[106:109], v[86:87], off offset:64
	global_load_dwordx4 v[110:113], v[88:89], off offset:64
	global_load_dwordx4 v[114:117], v[90:91], off offset:64
	global_load_dwordx4 v[118:121], v[86:87], off offset:128
	global_load_dwordx4 v[122:125], v[88:89], off offset:128
	global_load_dwordx4 v[126:129], v[90:91], off offset:128
	global_load_dwordx4 v[130:133], v[86:87], off offset:192
	global_load_dwordx4 v[134:137], v[88:89], off offset:192
	global_load_dwordx4 v[138:141], v[90:91], off offset:192
	global_load_dwordx4 v[142:145], v[86:87], off offset:256
	global_load_dwordx4 v[146:149], v[88:89], off offset:256
	global_load_dwordx4 v[150:153], v[90:91], off offset:256
	global_load_dwordx4 v[154:157], v[86:87], off offset:320
	global_load_dwordx4 v[158:161], v[88:89], off offset:320
	global_load_dwordx4 v[162:165], v[90:91], off offset:320
	global_load_dwordx4 v[166:169], v[86:87], off offset:384
	global_load_dwordx4 v[170:173], v[88:89], off offset:384
	global_load_dwordx4 v[174:177], v[90:91], off offset:384
	global_load_dwordx4 v[178:181], v[86:87], off offset:448
	global_load_dwordx4 v[182:185], v[88:89], off offset:448
	global_load_dwordx4 v[186:189], v[90:91], off offset:448
	s_waitcnt vmcnt(21)
	v_mfma_f32_16x16x32_bf16 v[36:39], v[98:101], v[92:95], v[36:39]
	v_mfma_f32_16x16x32_bf16 v[24:27], v[102:105], v[92:95], v[24:27]
	global_load_dwordx4 v[92:95], v[86:87], off offset:512
	global_load_dwordx4 v[98:101], v[88:89], off offset:512
	global_load_dwordx4 v[102:105], v[90:91], off offset:512
	s_waitcnt vmcnt(21)
	v_mfma_f32_16x16x32_bf16 v[36:39], v[110:113], v[106:109], v[36:39]
	v_mfma_f32_16x16x32_bf16 v[24:27], v[114:117], v[106:109], v[24:27]
	global_load_dwordx4 v[106:109], v[86:87], off offset:576
	global_load_dwordx4 v[110:113], v[88:89], off offset:576
	global_load_dwordx4 v[114:117], v[90:91], off offset:576
	s_waitcnt vmcnt(21)
	v_mfma_f32_16x16x32_bf16 v[36:39], v[122:125], v[118:121], v[36:39]
	v_mfma_f32_16x16x32_bf16 v[24:27], v[126:129], v[118:121], v[24:27]
	global_load_dwordx4 v[118:121], v[86:87], off offset:640
	global_load_dwordx4 v[122:125], v[88:89], off offset:640
	global_load_dwordx4 v[126:129], v[90:91], off offset:640
	s_waitcnt vmcnt(21)
	v_mfma_f32_16x16x32_bf16 v[36:39], v[134:137], v[130:133], v[36:39]
	v_mfma_f32_16x16x32_bf16 v[24:27], v[138:141], v[130:133], v[24:27]
	s_waitcnt vmcnt(18)
	v_mfma_f32_16x16x32_bf16 v[36:39], v[146:149], v[142:145], v[36:39]
	v_mfma_f32_16x16x32_bf16 v[24:27], v[150:153], v[142:145], v[24:27]
	s_waitcnt vmcnt(15)
	v_mfma_f32_16x16x32_bf16 v[36:39], v[158:161], v[154:157], v[36:39]
	v_mfma_f32_16x16x32_bf16 v[24:27], v[162:165], v[154:157], v[24:27]
	s_waitcnt vmcnt(12)
	v_mfma_f32_16x16x32_bf16 v[36:39], v[170:173], v[166:169], v[36:39]
	v_mfma_f32_16x16x32_bf16 v[24:27], v[174:177], v[166:169], v[24:27]
	s_waitcnt vmcnt(9)
	v_mfma_f32_16x16x32_bf16 v[36:39], v[182:185], v[178:181], v[36:39]
	v_mfma_f32_16x16x32_bf16 v[24:27], v[186:189], v[178:181], v[24:27]
	s_waitcnt vmcnt(6)
	v_mfma_f32_16x16x32_bf16 v[36:39], v[98:101], v[92:95], v[36:39]
	v_mfma_f32_16x16x32_bf16 v[24:27], v[102:105], v[92:95], v[24:27]
	s_waitcnt vmcnt(3)
	v_mfma_f32_16x16x32_bf16 v[36:39], v[110:113], v[106:109], v[36:39]
	v_mfma_f32_16x16x32_bf16 v[24:27], v[114:117], v[106:109], v[24:27]
	s_waitcnt vmcnt(0)
	v_mfma_f32_16x16x32_bf16 v[36:39], v[122:125], v[118:121], v[36:39]
	v_mfma_f32_16x16x32_bf16 v[24:27], v[126:129], v[118:121], v[24:27]
	s_nop 7
	s_nop 1
	ds_write_b128 v68, v[36:39]
	ds_write_b128 v68, v[24:27] offset:1024
	s_waitcnt lgkmcnt(0)
	s_waitcnt lgkmcnt(0)
	s_barrier
; __device__ __forceinline__ unsigned cvt_pk_bf16(float lo, float hi) { unsigned r; asm volatile("v_cvt_pk_bf16_f32 %0, %1, %2" : "=v"(r) : "v"(lo), "v"(hi)); return r; }
; template <int KSTEPS  >
; __device__ __forceinline__ void small_mma_ksplit(f32x4 (&acc)[2], const bf16_t* A, int lda, const bf16_t* Bt, int ldb, int n0, LAS unsigned char* lds, const SmallId& id) {
;     ...
;     acc[0] = (f32x4){0.f, 0.f, 0.f, 0.f}; acc[1] = acc[0];
; #pragma unroll
;     for (int w2 = 0; w2 < 8; ++w2) { acc[0] += red[((w2 * 8 + id.w) * 2 + 0) * 64 + lane]; acc[1] += red[((w2 * 8 + id.w) * 2 + 1) * 64 + lane]; }
;     asm volatile("s_waitcnt lgkmcnt(0)" ::: "memory"); __syncthreads();
; template <bool RES_F32, bool OUT_F32, int KSTEPS>
; __device__ __forceinline__ void small_res(const Params& p, LAS unsigned char* lds, const bf16_t* A, int lda, const bf16_t* Bt, int K, float* ssq_next, int G, int bx) {
;     ...
;         float s = 0.f;
; #pragma unroll
;         for (int nb = 0; nb < 2; ++nb) { const int col = n0 + 16 * nb + 4 * id.fq;
;             f32x4 r;
;             if (RES_F32) r = *(const f32x4*)(p.xs + (size_t)(id.row - MP) * DM + col);
;             else { const u32x2 w = *(const u32x2*)(XB + (size_t)id.row * DM + col); r = (f32x4){bf_lo(w.x), bf_hi(w.x), bf_lo(w.y), bf_hi(w.y)}; }
;             const f32x4 x = r + acc[nb];
;             if (OUT_F32) *(f32x4*)(p.out + (size_t)id.row * DM + col) = x;
;             else { u32x2 w; w.x = cvt_pk_bf16(x[0], x[1]); w.y = cvt_pk_bf16(x[2], x[3]); *(u32x2*)(XB + (size_t)id.row * DM + col) = w; }
;             s += (x[0] * x[0] + x[1] * x[1]) + (x[2] * x[2] + x[3] * x[3]); }
;         if (!OUT_F32) { s += __shfl_xor(s, 16); s += __shfl_xor(s, 32); if (id.fq == 0) atomicAdd(ssq_next + id.row, s); }
;     }
	ds_read_b128 v[0:3], v75
	s_waitcnt lgkmcnt(0)
	v_pk_add_f32 v[4:5], v[2:3], 0 op_sel_hi:[1,0]
	v_pk_add_f32 v[6:7], v[0:1], 0 op_sel_hi:[1,0]
	ds_read_b128 v[0:3], v75 offset:1024
	s_waitcnt lgkmcnt(0)
	v_pk_add_f32 v[8:9], v[2:3], 0 op_sel_hi:[1,0]
	v_pk_add_f32 v[10:11], v[0:1], 0 op_sel_hi:[1,0]
	ds_read_b128 v[0:3], v75 offset:16384
	s_waitcnt lgkmcnt(0)
	v_pk_add_f32 v[4:5], v[4:5], v[2:3]
	v_pk_add_f32 v[6:7], v[6:7], v[0:1]
	ds_read_b128 v[0:3], v75 offset:17408
	s_waitcnt lgkmcnt(0)
	v_pk_add_f32 v[8:9], v[8:9], v[2:3]
	v_pk_add_f32 v[10:11], v[10:11], v[0:1]
	ds_read_b128 v[0:3], v75 offset:32768
	s_waitcnt lgkmcnt(0)
	v_pk_add_f32 v[4:5], v[4:5], v[2:3]
	v_pk_add_f32 v[6:7], v[6:7], v[0:1]
	ds_read_b128 v[0:3], v75 offset:33792
	s_waitcnt lgkmcnt(0)
	v_pk_add_f32 v[8:9], v[8:9], v[2:3]
	v_pk_add_f32 v[10:11], v[10:11], v[0:1]
	ds_read_b128 v[0:3], v75 offset:49152
	s_waitcnt lgkmcnt(0)
	v_pk_add_f32 v[4:5], v[4:5], v[2:3]
	v_pk_add_f32 v[6:7], v[6:7], v[0:1]
	ds_read_b128 v[0:3], v75 offset:50176
	s_waitcnt lgkmcnt(0)
	v_pk_add_f32 v[8:9], v[8:9], v[2:3]
	v_pk_add_f32 v[10:11], v[10:11], v[0:1]
	ds_read_b128 v[0:3], v76
	s_waitcnt lgkmcnt(0)
	v_pk_add_f32 v[4:5], v[4:5], v[2:3]
	v_pk_add_f32 v[6:7], v[6:7], v[0:1]
	ds_read_b128 v[0:3], v77
	s_waitcnt lgkmcnt(0)
	v_pk_add_f32 v[8:9], v[8:9], v[2:3]
	v_pk_add_f32 v[10:11], v[10:11], v[0:1]
	ds_read_b128 v[0:3], v78
	s_waitcnt lgkmcnt(0)
	v_pk_add_f32 v[4:5], v[4:5], v[2:3]
	v_pk_add_f32 v[6:7], v[6:7], v[0:1]
	ds_read_b128 v[0:3], v79
	s_waitcnt lgkmcnt(0)
	v_pk_add_f32 v[8:9], v[8:9], v[2:3]
	v_pk_add_f32 v[10:11], v[10:11], v[0:1]
	ds_read_b128 v[0:3], v80
	s_waitcnt lgkmcnt(0)
	v_pk_add_f32 v[4:5], v[4:5], v[2:3]
	v_pk_add_f32 v[6:7], v[6:7], v[0:1]
	ds_read_b128 v[0:3], v81
	s_waitcnt lgkmcnt(0)
	v_pk_add_f32 v[8:9], v[8:9], v[2:3]
	v_pk_add_f32 v[10:11], v[10:11], v[0:1]
	ds_read_b128 v[0:3], v82
	s_waitcnt lgkmcnt(0)
	v_pk_add_f32 v[4:5], v[4:5], v[2:3]
	v_pk_add_f32 v[6:7], v[6:7], v[0:1]
	ds_read_b128 v[0:3], v83
	s_waitcnt lgkmcnt(0)
	s_waitcnt lgkmcnt(0)
	s_barrier
	s_mul_i32 exec_lo, s32, -1
	s_mov_b32 exec_hi, exec_lo
	v_pk_add_f32 v[2:3], v[8:9], v[2:3]
	v_lshl_or_b32 v8, s7, 5, v84
	v_ashrrev_i32_e32 v9, 31, v8
	v_lshl_add_u64 v[8:9], v[8:9], 1, v[64:65]
	v_pk_add_f32 v[0:1], v[10:11], v[0:1]
	global_load_dwordx2 v[10:11], v[8:9], off
	s_waitcnt vmcnt(0) lgkmcnt(0)
	v_lshlrev_b32_e32 v12, 16, v10
	v_and_b32_e32 v13, 0xffff0000, v10
	v_lshlrev_b32_e32 v10, 16, v11
	v_and_b32_e32 v11, 0xffff0000, v11
	v_pk_add_f32 v[4:5], v[4:5], v[10:11]
	v_pk_add_f32 v[6:7], v[6:7], v[12:13]
	s_nop 0
	v_cvt_pk_bf16_f32 v10, v6, v7
	v_cvt_pk_bf16_f32 v11, v4, v5
	v_mul_f32_e32 v7, v7, v7
	v_mul_f32_e32 v5, v5, v5
	v_fmac_f32_e32 v7, v6, v6
	v_fmac_f32_e32 v5, v4, v4
	global_store_dwordx2 v[8:9], v[10:11], off
	v_add_f32_e32 v10, v7, v5
	global_load_dwordx2 v[4:5], v[8:9], off offset:32
	s_waitcnt vmcnt(0) lgkmcnt(0)
	v_lshlrev_b32_e32 v6, 16, v4
	v_and_b32_e32 v7, 0xffff0000, v4
	v_lshlrev_b32_e32 v4, 16, v5
	v_and_b32_e32 v5, 0xffff0000, v5
	v_pk_add_f32 v[0:1], v[0:1], v[6:7]
	v_pk_add_f32 v[2:3], v[2:3], v[4:5]
	v_cvt_pk_bf16_f32 v4, v0, v1
	v_mul_f32_e32 v1, v1, v1
	v_fmac_f32_e32 v1, v0, v0
	v_mul_f32_e32 v0, v3, v3
	v_cvt_pk_bf16_f32 v5, v2, v3
	v_fmac_f32_e32 v0, v2, v2
	v_and_b32_e32 v2, 64, v225
	v_add_f32_e32 v0, v1, v0
	v_xor_b32_e32 v1, 16, v225
	v_add_u32_e32 v2, 64, v2
	v_cmp_lt_i32_e64 s[0:1], v1, v2
	v_add_f32_e32 v0, v10, v0
	global_store_dwordx2 v[8:9], v[4:5], off offset:32
	v_cndmask_b32_e64 v1, v225, v1, s[0:1]
	v_lshlrev_b32_e32 v1, 2, v1
	ds_bpermute_b32 v1, v1, v0
	s_waitcnt lgkmcnt(0)
	v_add_f32_e32 v0, v0, v1
	v_xor_b32_e32 v1, 32, v225
	v_cmp_lt_i32_e64 s[0:1], v1, v2
	s_nop 1
	v_cndmask_b32_e64 v1, v225, v1, s[0:1]
	v_lshlrev_b32_e32 v1, 2, v1
	ds_bpermute_b32 v1, v1, v0
	s_and_saveexec_b64 s[0:1], vcc
	s_cbranch_execz .LBB0_1253
	s_waitcnt lgkmcnt(0)
	v_add_f32_e32 v0, v0, v1
	global_atomic_add_f32 v[66:67], v0, off
	s_branch .LBB0_1253
